# ret+mamba scan unit boundaries no longer drain output stores (epilogue wait before stores, top wait removed, first-barrier wait only for sample units)
# baseline (speedup 1.0000x reference)
; __device__ __forceinline__ void ret_block(ArgsP a_, unsigned char* smem) { const ArgsP a = a_;
;     ...
;     const int np = cb < 256 ? 33 : 0;
;     const int s0 = cb < 256 ? cb : cb - 256;
;     const int nsmp = (4096 - (cb % 256) + G - 1) / G;
;     const int nunits = np + nsmp;
;     f32x4 S[2][4]; f32x4 O[2];
;     u32x4 qpre[4], kpre[4]; bf16_t vpre[8];
;     const int vv = tid & 63, jg = tid >> 6;
;     ...
;     (void)s0;
;     if (nunits > 0) RT_LOAD(0);
;     const int ntot_ = np + nsmp * REP_SMP;
.LBB0_230:
	s_mov_b64 s[94:95], s[56:57]
	s_andn2_b64 vcc, exec, s[34:35]
	s_cbranch_vccnz .LBB0_306
	v_lshrrev_b32_e32 v42, 4, v18
	v_lshlrev_b32_e32 v43, 5, v19
	v_lshlrev_b32_e32 v16, 2, v42
	v_or_b32_e32 v40, v16, v43
	v_ashrrev_i32_e32 v41, 31, v40
	v_lshlrev_b64 v[98:99], 11, v[40:41]
	v_or_b32_e32 v40, 16, v40
	v_ashrrev_i32_e32 v41, 31, v40
	v_lshlrev_b64 v[100:101], 11, v[40:41]
	v_mul_u32_u24_e32 v41, 0x90, v18
	v_lshlrev_b32_e32 v44, 4, v19
	v_readlane_b32 s35, v254, 26
	v_readlane_b32 s48, v254, 27
	v_readlane_b32 s34, v254, 28
	v_add3_u32 v118, s35, v41, v44
	v_lshlrev_b32_e32 v41, 2, v97
	v_readlane_b32 s67, v254, 29
	v_add_u32_e32 v120, s48, v41
	v_add_u32_e32 v122, s34, v41
	v_add_u32_e32 v123, s67, v41
	v_and_b32_e32 v41, 0x7f, v97
	v_ashrrev_i32_e32 v44, 7, v97
	s_movk_i32 s34, 0x100
	v_lshlrev_b32_e32 v46, 2, v41
	v_mul_u32_u24_e32 v41, 0x120, v41
	v_lshlrev_b32_e32 v47, 5, v44
	v_readlane_b32 s68, v254, 30
	v_and_b32_e32 v96, 15, v97
	v_cmp_gt_i32_e64 s[42:43], s34, v97
	v_add3_u32 v124, s68, v41, v47
	v_and_b32_e32 v41, 0xffffffc0, v97
	v_lshlrev_b32_e32 v42, 3, v42
	v_readlane_b32 s34, v254, 31
	v_lshl_or_b32 v48, v44, 4, v96
	s_movk_i32 s69, 0x210
	v_add3_u32 v41, s34, v41, v42
	v_lshlrev_b32_e32 v42, 1, v19
	v_and_b32_e32 v49, 2, v42
	v_mul_lo_u32 v42, v48, s69
	v_and_b32_e32 v50, 48, v18
	v_cmp_le_i32_e64 s[44:45], v49, v44
	v_cmp_ge_i32_e64 s[46:47], v49, v44
	v_add3_u32 v126, 0, v42, v50
	v_lshlrev_b32_e32 v42, 4, v49
	v_lshlrev_b32_e32 v49, 6, v49
	v_add3_u32 v128, s48, v50, v49
	v_or_b32_e32 v49, v42, v16
	v_add_u32_e32 v51, s34, v50
	s_movk_i32 s34, 0x90
	v_or_b32_e32 v55, 2, v49
	v_mul_lo_u32 v54, v48, s34
	v_readlane_b32 s49, v254, 32
	v_cmp_gt_i32_e64 s[52:53], v55, v48
	v_or_b32_e32 v55, 3, v49
	v_add_u32_e32 v54, s49, v54
	v_cmp_gt_i32_e64 s[54:55], v55, v48
	v_or_b32_e32 v55, 16, v49
	v_lshl_add_u32 v125, v48, 2, s48
	v_or_b32_e32 v52, v42, v96
	v_cmp_gt_i32_e64 s[48:49], v49, v48
	v_cmp_lt_i32_e64 s[50:51], v49, v48
	v_lshl_add_u32 v129, v49, 1, v54
	v_cmp_gt_i32_e64 s[56:57], v55, v48
	v_cmp_lt_i32_e64 s[58:59], v55, v48
	v_or_b32_e32 v55, 18, v49
	v_or_b32_e32 v49, 19, v49
	v_lshlrev_b32_e32 v40, 3, v97
	v_lshlrev_b32_e32 v117, 3, v19
	v_mul_u32_u24_e32 v53, 0x210, v52
	v_cmp_gt_i32_e64 s[62:63], v49, v48
	v_mul_u32_u24_e32 v49, 0x90, v52
	v_and_b32_e32 v52, 48, v97
	v_lshlrev_b32_e32 v19, 7, v19
	v_and_b32_e32 v116, 0xf8, v40
	v_add3_u32 v131, s67, v52, v19
	v_or_b32_e32 v19, v43, v96
	v_lshl_add_u32 v40, v116, 1, 0
	v_mul_lo_u32 v43, v19, s34
	v_or_b32_e32 v19, 16, v19
	v_ashrrev_i32_e32 v52, 3, v97
	v_ashrrev_i32_e32 v133, 5, v97
	v_cmp_gt_i32_e64 s[60:61], v55, v48
	v_add_u32_e32 v48, s35, v50
	v_mul_lo_u32 v19, v19, s34
	v_bfi_b32 v132, -16, v52, v97
	v_mad_u64_u32 v[102:103], s[34:35], v133, s69, v[40:41]
	v_add_u32_e32 v52, 0x200, v97
	v_ashrrev_i32_e32 v103, 5, v52
	v_mad_u64_u32 v[104:105], s[34:35], v103, s69, v[40:41]
	v_add_u32_e32 v52, 0x400, v97
	v_ashrrev_i32_e32 v105, 5, v52
	s_add_u32 s26, s26, 0x17ee0000
	v_mad_u64_u32 v[106:107], s[34:35], v105, s69, v[40:41]
	v_add_u32_e32 v52, 0x600, v97
	s_addc_u32 s27, s27, 0
	v_ashrrev_i32_e32 v107, 5, v52
	s_abs_i32 s82, s66
	v_mad_u64_u32 v[108:109], s[34:35], v107, s69, v[40:41]
	v_cvt_f32_u32_e32 v40, s82
	s_sub_i32 s35, 0, s82
	v_lshlrev_b32_e32 v45, 6, v44
	s_movk_i32 s34, 0x2100
	v_rcp_iflag_f32_e32 v40, v40
	s_ashr_i32 s80, s74, 5
	v_mul_u32_u24_e32 v47, 0x210, v96
	v_add3_u32 v127, 0, v53, v50
	v_mul_f32_e32 v40, 0x4f7ffffe, v40
	v_cvt_u32_f32_e32 v40, v40
	v_add_u32_e32 v130, v54, v50
	v_add_u32_e32 v50, s68, v50
	v_mul_u32_u24_e32 v54, 0x90, v96
	v_readfirstlane_b32 s66, v40
	s_mul_i32 s35, s35, s66
	s_mul_hi_u32 s35, s66, s35
	v_mul_lo_u32 v44, v44, s34
	s_add_i32 s83, s66, s35
	s_sub_i32 s35, s64, s65
	v_mov_b32_e32 v40, 0
	v_lshlrev_b32_e32 v110, 1, v18
	v_add_u32_e32 v18, 0, v45
	s_mul_i32 s81, s80, 0x810
	v_cmp_gt_i32_e64 s[40:41], 64, v97
	v_add_u32_e32 v119, 1, v97
	v_not_b32_e32 v121, v97
	v_or_b32_e32 v109, 1, v117
	v_or_b32_e32 v134, 2, v117
	v_or_b32_e32 v135, 3, v117
	v_or_b32_e32 v136, 4, v117
	v_or_b32_e32 v137, 5, v117
	v_or_b32_e32 v138, 6, v117
	v_or_b32_e32 v139, 7, v117
	v_add3_u32 v140, 0, v46, v44
	v_add3_u32 v141, 0, v44, v46
	s_mov_b32 s34, 0
	s_sub_i32 s84, 0, s77
	s_sub_i32 s85, s35, s77
	v_add_u32_e32 v142, 0x26900, v18
	v_add_u32_e32 v143, v41, v47
	v_add_u32_e32 v144, v48, v49
	v_add_u32_e32 v145, v50, v43
	v_add_u32_e32 v147, v48, v54
	v_add_u32_e32 v164, v50, v19
	v_lshlrev_b32_e32 v112, 1, v16
	v_lshlrev_b32_e32 v114, 1, v42
	v_add_u32_e32 v165, v51, v53
	v_mov_b32_e32 v41, v40
	v_mov_b32_e32 v42, v40
	v_mov_b32_e32 v43, v40
	v_mov_b32_e32 v44, v40
	v_mov_b32_e32 v45, v40
	v_mov_b32_e32 v46, v40
	v_mov_b32_e32 v47, v40
	v_mov_b32_e32 v48, v40
	v_mov_b32_e32 v49, v40
	v_mov_b32_e32 v50, v40
	v_mov_b32_e32 v51, v40
	v_mov_b32_e32 v52, v40
	v_mov_b32_e32 v53, v40
	v_mov_b32_e32 v54, v40
	v_mov_b32_e32 v55, v40
	v_mov_b32_e32 v56, v40
	v_mov_b32_e32 v57, v40
	v_mov_b32_e32 v58, v40
	v_mov_b32_e32 v59, v40
	v_mov_b32_e32 v60, v40
	v_mov_b32_e32 v61, v40
	v_mov_b32_e32 v62, v40
	v_mov_b32_e32 v63, v40
	v_mov_b32_e32 v64, v40
	v_mov_b32_e32 v65, v40
	v_mov_b32_e32 v66, v40
	v_mov_b32_e32 v67, v40
	v_mov_b32_e32 v68, v40
	v_mov_b32_e32 v69, v40
	v_mov_b32_e32 v70, v40
	v_mov_b32_e32 v71, v40
	s_waitcnt vmcnt(0)
	s_branch .LBB0_233

; __device__ __forceinline__ void ret_block(ArgsP a_, unsigned char* smem) { const ArgsP a = a_;
;     ...
;         *(u32x4*)(VT + vv * LJ + 8 * jg) = (u32x4){(unsigned)vpre[0] | ((unsigned)vpre[1] << 16), (unsigned)vpre[2] | ((unsigned)vpre[3] << 16), (unsigned)vpre[4] | ((unsigned)vpre[5] << 16), (unsigned)vpre[6] | ((unsigned)vpre[7] << 16)};
.LBB0_242:
	s_cmp_eq_u32 s89, 64
	s_cbranch_scc1 .Lret_mask_full
	v_cmp_gt_i32_e32 vcc, s89, v133
	s_nop 1
	v_cndmask_b32_e32 v3, 0, v3, vcc
	v_cndmask_b32_e32 v2, 0, v2, vcc
	v_cndmask_b32_e32 v1, 0, v1, vcc
	v_cndmask_b32_e32 v0, 0, v0, vcc
	v_cndmask_b32_e32 v7, 0, v7, vcc
	v_cndmask_b32_e32 v6, 0, v6, vcc
	v_cndmask_b32_e32 v5, 0, v5, vcc
	v_cndmask_b32_e32 v4, 0, v4, vcc
	v_cmp_gt_i32_e32 vcc, s89, v103
	s_nop 1
	v_cndmask_b32_e32 v11, 0, v11, vcc
	v_cndmask_b32_e32 v10, 0, v10, vcc
	v_cndmask_b32_e32 v9, 0, v9, vcc
	v_cndmask_b32_e32 v8, 0, v8, vcc
	v_cndmask_b32_e32 v15, 0, v15, vcc
	v_cndmask_b32_e32 v14, 0, v14, vcc
	v_cndmask_b32_e32 v13, 0, v13, vcc
	v_cndmask_b32_e32 v12, 0, v12, vcc
	v_cmp_gt_i32_e32 vcc, s89, v105
	s_nop 1
	v_cndmask_b32_e32 v23, 0, v213, vcc
	v_cndmask_b32_e32 v22, 0, v212, vcc
	v_cndmask_b32_e32 v21, 0, v211, vcc
	v_cndmask_b32_e32 v20, 0, v210, vcc
	v_cndmask_b32_e32 v27, 0, v27, vcc
	v_cndmask_b32_e32 v26, 0, v26, vcc
	v_cndmask_b32_e32 v25, 0, v25, vcc
	v_cndmask_b32_e32 v24, 0, v24, vcc
	v_cmp_gt_i32_e32 vcc, s89, v107
	s_nop 1
	v_cndmask_b32_e32 v31, 0, v31, vcc
	v_cndmask_b32_e32 v30, 0, v30, vcc
	v_cndmask_b32_e32 v29, 0, v29, vcc
	v_cndmask_b32_e32 v28, 0, v28, vcc
	v_cndmask_b32_e32 v35, 0, v35, vcc
	v_cndmask_b32_e32 v34, 0, v34, vcc
	v_cndmask_b32_e32 v33, 0, v33, vcc
	v_cndmask_b32_e32 v32, 0, v32, vcc
	v_cmp_gt_i32_e32 vcc, s89, v117
	v_lshlrev_b32_e32 v18, 16, v203
	s_nop 0
	v_cndmask_b32_e32 v16, 0, v202, vcc
	v_cmp_gt_i32_e32 vcc, s89, v109
	s_nop 1
	v_cndmask_b32_e32 v18, 0, v18, vcc
	s_nop 0
	v_or_b32_e32 v36, v18, v16
	v_cmp_gt_i32_e32 vcc, s89, v134
	v_lshlrev_b32_e32 v18, 16, v205
	s_nop 0
	v_cndmask_b32_e32 v16, 0, v204, vcc
	v_cmp_gt_i32_e32 vcc, s89, v135
	s_nop 1
	v_cndmask_b32_e32 v18, 0, v18, vcc
	s_nop 0
	v_or_b32_e32 v37, v18, v16
	v_cmp_gt_i32_e32 vcc, s89, v136
	v_lshlrev_b32_e32 v18, 16, v207
	s_nop 0
	v_cndmask_b32_e32 v16, 0, v206, vcc
	v_cmp_gt_i32_e32 vcc, s89, v137
	s_nop 1
	v_cndmask_b32_e32 v18, 0, v18, vcc
	s_nop 0
	v_or_b32_e32 v38, v18, v16
	v_cmp_gt_i32_e32 vcc, s89, v138
	v_lshlrev_b32_e32 v18, 16, v209
	s_nop 0
	v_cndmask_b32_e32 v16, 0, v208, vcc
	v_cmp_gt_i32_e32 vcc, s89, v139
	s_nop 1
	v_cndmask_b32_e32 v18, 0, v18, vcc
	s_nop 0
	v_or_b32_e32 v39, v18, v16
	s_branch .Lret_mask_done

; __device__ __forceinline__ unsigned cvt_pk_bf16(float lo, float hi) { unsigned r; asm("v_cvt_pk_bf16_f32 %0, %1, %2" : "=v"(r) : "v"(lo), "v"(hi)); return r; }
; template <int DK, int DV, bool SEPQ> ...
;     ...
;         for (int vt = 0; vt < NVT; ++vt) { const f32x4 s = S[ct][vt]; u32x2 w; w.x = cvt_pk_bf16(s[0], s[1]); w.y = cvt_pk_bf16(s[2], s[3]);
;             *(u32x2*)(ST + (16 * vt + fr) * LQ + 16 * (wid * NCTW + ct) + 4 * fq) = w; }
;     __syncthreads();
; __device__ __forceinline__ void ret_block(ArgsP a_, unsigned char* smem) { const ArgsP a = a_;
;     ...
;         if (tid < 256) SDEC[tid] = __expf((float)len * lgam);
.LBB0_263:
	s_cmp_lg_u32 s89, 8
	s_cbranch_scc1 .Lret_st_nowait
	s_waitcnt vmcnt(0)
.Lret_st_nowait:
	v_cvt_pk_bf16_f32 v0, v40, v41
	v_cvt_pk_bf16_f32 v1, v42, v43
	v_cvt_pk_bf16_f32 v2, v56, v57
	v_cvt_pk_bf16_f32 v3, v58, v59
	ds_write2_b64 v143, v[0:1], v[2:3] offset1:4
	v_cvt_pk_bf16_f32 v4, v44, v45
	v_cvt_pk_bf16_f32 v5, v46, v47
	v_cvt_pk_bf16_f32 v6, v60, v61
	v_cvt_pk_bf16_f32 v7, v62, v63
	v_add_u32_e32 v9, 0x2000, v143
	ds_write2_b64 v9, v[4:5], v[6:7] offset0:32 offset1:36
	v_cvt_pk_bf16_f32 v0, v48, v49
	v_cvt_pk_bf16_f32 v1, v50, v51
	v_cvt_pk_bf16_f32 v2, v64, v65
	v_cvt_pk_bf16_f32 v3, v66, v67
	v_add_u32_e32 v8, 0x4000, v143
	ds_write2_b64 v8, v[0:1], v[2:3] offset0:64 offset1:68
	v_cvt_pk_bf16_f32 v4, v52, v53
	v_cvt_pk_bf16_f32 v5, v54, v55
	v_cvt_pk_bf16_f32 v6, v68, v69
	v_cvt_pk_bf16_f32 v7, v70, v71
	v_add_u32_e32 v9, 0x6000, v143
	ds_write2_b64 v9, v[4:5], v[6:7] offset0:96 offset1:100
	s_waitcnt lgkmcnt(0)
	s_barrier
	ds_write_b128 v118, v[36:39]
	s_and_saveexec_b64 s[64:65], s[42:43]
	s_cbranch_execz .Lret_sdec_skip
	v_cvt_f32_u32_e32 v18, s89
	v_mul_f32_e32 v16, v16, v18
	v_mul_f32_e32 v16, 0x3fb8aa3b, v16
	v_exp_f32_e32 v16, v16
	ds_write_b32 v123, v16

; __device__ __forceinline__ unsigned cvt_pk_bf16(float lo, float hi) { unsigned r; asm("v_cvt_pk_bf16_f32 %0, %1, %2" : "=v"(r) : "v"(lo), "v"(hi)); return r; }
; template <int DK, int DV, bool SEPQ> ...
;     ...
;         for (int ks = 0; ks < DK / 32; ++ks) {
;             const bf16x8 qf = *(const bf16x8*)(QA + (16 * m + fr) * LQ + 32 * ks + 8 * fq);
;             if (do0) { const bf16x8 kf = *(const bf16x8*)(KB + (16 * n0 + fr) * LQ + 32 * ks + 8 * fq); acc0 = __builtin_amdgcn_mfma_f32_16x16x32_bf16(kf, qf, acc0, 0, 0, 0); }
;             if (do1) { const bf16x8 kf = *(const bf16x8*)(KB + (16 * n1 + fr) * LQ + 32 * ks + 8 * fq); acc1 = __builtin_amdgcn_mfma_f32_16x16x32_bf16(kf, qf, acc1, 0, 0, 0); }
;             bf16x8 qs = qf; if (SEPQ) qs = *(const bf16x8*)(QS + (16 * m + fr) * LQ + 32 * ks + 8 * fq);
; #pragma unroll
;             for (int vt = 0; vt < NVTW; ++vt) { const bf16x8 sf = *(const bf16x8*)(ST + (16 * (hw * NVTW + vt) + fr) * LQ + 32 * ks + 8 * fq); O[vt] = __builtin_amdgcn_mfma_f32_16x16x32_bf16(sf, qs, O[vt], 0, 0, 0); }
;         }
; __device__ __forceinline__ void ret_block(ArgsP a_, unsigned char* smem) { const ArgsP a = a_;
;     ...
;         { const int cp = tid & 127, jq = tid >> 7;
;           float dj[16];
; #pragma unroll
;           for (int q4 = 0; q4 < 4; ++q4) { const f32x4 t = *(const f32x4*)(DECJ + 16 * jq + 4 * q4); dj[4 * q4] = t[0]; dj[4 * q4 + 1] = t[1]; dj[4 * q4 + 2] = t[2]; dj[4 * q4 + 3] = t[3]; }
;           unsigned lo[8], hi[8];
; #pragma unroll
;           for (int e = 0; e < 8; ++e) { const int j = 16 * jq + 2 * e; const unsigned w0 = *(const unsigned*)(KB + j * LQ + 2 * cp), w1 = *(const unsigned*)(KB + (j + 1) * LQ + 2 * cp);
;               lo[e] = cvt_pk_bf16(__uint_as_float(w0 << 16) * dj[2 * e], __uint_as_float(w1 << 16) * dj[2 * e + 1]);
;               hi[e] = cvt_pk_bf16(__uint_as_float(w0 & 0xffff0000u) * dj[2 * e], __uint_as_float(w1 & 0xffff0000u) * dj[2 * e + 1]); }
;           *(u32x4*)(KT + (2 * cp) * LJ + 16 * jq) = (u32x4){lo[0], lo[1], lo[2], lo[3]}; *(u32x4*)(KT + (2 * cp) * LJ + 16 * jq + 8) = (u32x4){lo[4], lo[5], lo[6], lo[7]};
;           *(u32x4*)(KT + (2 * cp + 1) * LJ + 16 * jq) = (u32x4){hi[0], hi[1], hi[2], hi[3]}; *(u32x4*)(KT + (2 * cp + 1) * LJ + 16 * jq + 8) = (u32x4){hi[4], hi[5], hi[6], hi[7]}; }
.LBB0_269:
	ds_read_b128 v[214:217], v142
	ds_read_b128 v[218:221], v142 offset:16
	ds_read_b128 v[222:225], v142 offset:32
	ds_read_b128 v[226:229], v142 offset:48
	ds_read_b32 v230, v140 offset:33792
	ds_read_b32 v231, v141 offset:34320
	ds_read_b32 v232, v140 offset:34848
	ds_read_b32 v233, v141 offset:35376
	ds_read_b32 v234, v140 offset:35904
	ds_read_b32 v235, v141 offset:36432
	ds_read_b32 v236, v140 offset:36960
	ds_read_b32 v237, v141 offset:37488
	ds_read_b32 v238, v140 offset:38016
	ds_read_b32 v239, v141 offset:38544
	ds_read_b32 v240, v140 offset:39072
	s_waitcnt lgkmcnt(10)
	v_lshlrev_b32_e32 v19, 16, v230
	ds_read_b32 v241, v141 offset:39600
	ds_read_b32 v242, v140 offset:40128
	ds_read_b32 v243, v141 offset:40656
	ds_read_b32 v244, v140 offset:41184
	ds_read_b32 v245, v141 offset:41712
	s_waitcnt lgkmcnt(14)
	v_lshlrev_b32_e32 v80, 16, v231
	v_and_b32_e32 v16, 0xffff0000, v230
	v_and_b32_e32 v18, 0xffff0000, v231
	v_mul_f32_e32 v16, v214, v16
	v_mul_f32_e32 v18, v215, v18
	v_mul_f32_e32 v19, v214, v19
	v_cvt_pk_bf16_f32 v72, v16, v18
	v_mul_f32_e32 v80, v215, v80
	v_cvt_pk_bf16_f32 v80, v19, v80
	s_waitcnt lgkmcnt(13)
	v_lshlrev_b32_e32 v19, 16, v232
	s_waitcnt lgkmcnt(12)
	v_lshlrev_b32_e32 v73, 16, v233
	v_and_b32_e32 v16, 0xffff0000, v232
	v_and_b32_e32 v18, 0xffff0000, v233
	v_mul_f32_e32 v73, v217, v73
	v_mul_f32_e32 v16, v216, v16
	v_mul_f32_e32 v18, v217, v18
	v_mul_f32_e32 v19, v216, v19
	v_cvt_pk_bf16_f32 v81, v19, v73
	v_cvt_pk_bf16_f32 v73, v16, v18
	s_waitcnt lgkmcnt(11)
	v_lshlrev_b32_e32 v19, 16, v234
	s_waitcnt lgkmcnt(10)
	v_lshlrev_b32_e32 v74, 16, v235
	v_and_b32_e32 v16, 0xffff0000, v234
	v_and_b32_e32 v18, 0xffff0000, v235
	v_mul_f32_e32 v74, v219, v74
	v_mul_f32_e32 v16, v218, v16
	v_mul_f32_e32 v18, v219, v18
	v_mul_f32_e32 v19, v218, v19
	v_cvt_pk_bf16_f32 v82, v19, v74
	v_cvt_pk_bf16_f32 v74, v16, v18
	s_waitcnt lgkmcnt(9)
	v_lshlrev_b32_e32 v19, 16, v236
	s_waitcnt lgkmcnt(8)
	v_lshlrev_b32_e32 v75, 16, v237
	v_and_b32_e32 v16, 0xffff0000, v236
	v_and_b32_e32 v18, 0xffff0000, v237
	v_mul_f32_e32 v75, v221, v75
	v_mul_f32_e32 v16, v220, v16
	v_mul_f32_e32 v18, v221, v18
	v_mul_f32_e32 v19, v220, v19
	v_cvt_pk_bf16_f32 v83, v19, v75
	v_cvt_pk_bf16_f32 v75, v16, v18
	s_waitcnt lgkmcnt(7)
	v_lshlrev_b32_e32 v19, 16, v238
	s_waitcnt lgkmcnt(6)
	v_lshlrev_b32_e32 v88, 16, v239
	v_and_b32_e32 v16, 0xffff0000, v238
	v_and_b32_e32 v18, 0xffff0000, v239
	v_mul_f32_e32 v16, v222, v16
	v_mul_f32_e32 v18, v223, v18
	v_mul_f32_e32 v19, v222, v19
	v_cvt_pk_bf16_f32 v84, v16, v18
	v_mul_f32_e32 v88, v223, v88
	v_cvt_pk_bf16_f32 v88, v19, v88
	s_waitcnt lgkmcnt(5)
	v_lshlrev_b32_e32 v19, 16, v240
	s_waitcnt lgkmcnt(4)
	v_lshlrev_b32_e32 v85, 16, v241
	v_and_b32_e32 v16, 0xffff0000, v240
	v_and_b32_e32 v18, 0xffff0000, v241
	v_mul_f32_e32 v85, v225, v85
	v_mul_f32_e32 v16, v224, v16
	v_mul_f32_e32 v18, v225, v18
	v_mul_f32_e32 v19, v224, v19
	v_cvt_pk_bf16_f32 v89, v19, v85
	v_cvt_pk_bf16_f32 v85, v16, v18
	s_waitcnt lgkmcnt(3)
	v_lshlrev_b32_e32 v19, 16, v242
	s_waitcnt lgkmcnt(2)
	v_lshlrev_b32_e32 v86, 16, v243
	v_and_b32_e32 v16, 0xffff0000, v242
	v_and_b32_e32 v18, 0xffff0000, v243
	v_mul_f32_e32 v86, v227, v86
	v_mul_f32_e32 v16, v226, v16
	v_mul_f32_e32 v18, v227, v18
	v_mul_f32_e32 v19, v226, v19
	v_cvt_pk_bf16_f32 v90, v19, v86
	v_cvt_pk_bf16_f32 v86, v16, v18
	s_waitcnt lgkmcnt(1)
	v_lshlrev_b32_e32 v19, 16, v244
	s_waitcnt lgkmcnt(0)
	v_lshlrev_b32_e32 v76, 16, v245
	v_and_b32_e32 v16, 0xffff0000, v244
	v_and_b32_e32 v18, 0xffff0000, v245
	v_mul_f32_e32 v19, v228, v19
	v_mul_f32_e32 v16, v228, v16
	v_mul_f32_e32 v18, v229, v18
	v_mul_f32_e32 v76, v229, v76
	v_cvt_pk_bf16_f32 v91, v19, v76
	v_cvt_pk_bf16_f32 v87, v16, v18
	ds_write_b128 v124, v[80:83]
	ds_write_b128 v124, v[88:91] offset:16
	ds_write_b128 v124, v[72:75] offset:144
	ds_write_b128 v124, v[84:87] offset:160
	s_waitcnt lgkmcnt(0)
	ds_read_b32 v92, v125
	ds_read_b128 v[214:217], v126
	ds_read_b128 v[218:221], v127 offset:33792
	ds_read_b128 v[222:225], v127 offset:42240
	ds_read_b128 v[226:229], v165
	ds_read_b128 v[230:233], v165 offset:8448
	ds_read_b128 v[166:169], v126 offset:64
	ds_read_b128 v[170:173], v127 offset:33856
	ds_read_b128 v[174:177], v127 offset:42304
	ds_read_b128 v[178:181], v165 offset:64
	ds_read_b128 v[182:185], v165 offset:8512
	s_waitcnt lgkmcnt(5)
	v_mfma_f32_16x16x32_bf16 v[76:79], v[218:221], v[214:217], 0
	v_mfma_f32_16x16x32_bf16 v[72:75], v[222:225], v[214:217], 0
	v_mfma_f32_16x16x32_bf16 v[80:83], v[226:229], v[214:217], 0
	v_mfma_f32_16x16x32_bf16 v[84:87], v[230:233], v[214:217], 0
	ds_read_b128 v[214:217], v126 offset:128
	ds_read_b128 v[218:221], v127 offset:33920
	ds_read_b128 v[222:225], v127 offset:42368
	ds_read_b128 v[226:229], v165 offset:128
	ds_read_b128 v[230:233], v165 offset:8576
	s_waitcnt lgkmcnt(5)
	v_mfma_f32_16x16x32_bf16 v[76:79], v[170:173], v[166:169], v[76:79]
	v_mfma_f32_16x16x32_bf16 v[72:75], v[174:177], v[166:169], v[72:75]
	v_mfma_f32_16x16x32_bf16 v[80:83], v[178:181], v[166:169], v[80:83]
	v_mfma_f32_16x16x32_bf16 v[84:87], v[182:185], v[166:169], v[84:87]
	ds_read_b128 v[166:169], v126 offset:192
	ds_read_b128 v[170:173], v127 offset:33984
	ds_read_b128 v[174:177], v127 offset:42432
	ds_read_b128 v[178:181], v165 offset:192
	ds_read_b128 v[182:185], v165 offset:8640
	s_waitcnt lgkmcnt(5)
	v_mfma_f32_16x16x32_bf16 v[76:79], v[218:221], v[214:217], v[76:79]
	v_mfma_f32_16x16x32_bf16 v[72:75], v[222:225], v[214:217], v[72:75]
	v_mfma_f32_16x16x32_bf16 v[80:83], v[226:229], v[214:217], v[80:83]
	v_mfma_f32_16x16x32_bf16 v[84:87], v[230:233], v[214:217], v[84:87]
	ds_read_b128 v[214:217], v126 offset:256
	ds_read_b128 v[218:221], v127 offset:34048
	ds_read_b128 v[222:225], v127 offset:42496
	ds_read_b128 v[226:229], v165 offset:256
	ds_read_b128 v[230:233], v165 offset:8704
	s_waitcnt lgkmcnt(5)
; __device__ __forceinline__ unsigned cvt_pk_bf16(float lo, float hi) { unsigned r; asm("v_cvt_pk_bf16_f32 %0, %1, %2" : "=v"(r) : "v"(lo), "v"(hi)); return r; }
; template <int DK, int DV, bool SEPQ> ...
;     ...
;         for (int ks = 0; ks < DK / 32; ++ks) {
;             const bf16x8 qf = *(const bf16x8*)(QA + (16 * m + fr) * LQ + 32 * ks + 8 * fq);
;             if (do0) { const bf16x8 kf = *(const bf16x8*)(KB + (16 * n0 + fr) * LQ + 32 * ks + 8 * fq); acc0 = __builtin_amdgcn_mfma_f32_16x16x32_bf16(kf, qf, acc0, 0, 0, 0); }
;             if (do1) { const bf16x8 kf = *(const bf16x8*)(KB + (16 * n1 + fr) * LQ + 32 * ks + 8 * fq); acc1 = __builtin_amdgcn_mfma_f32_16x16x32_bf16(kf, qf, acc1, 0, 0, 0); }
;             bf16x8 qs = qf; if (SEPQ) qs = *(const bf16x8*)(QS + (16 * m + fr) * LQ + 32 * ks + 8 * fq);
; #pragma unroll
;             for (int vt = 0; vt < NVTW; ++vt) { const bf16x8 sf = *(const bf16x8*)(ST + (16 * (hw * NVTW + vt) + fr) * LQ + 32 * ks + 8 * fq); O[vt] = __builtin_amdgcn_mfma_f32_16x16x32_bf16(sf, qs, O[vt], 0, 0, 0); }
;         }
; #pragma unroll
;         for (int nn = 0; nn < 2; ++nn) {
;             const int n = 2 * hw + nn; const f32x4 acc = nn == 0 ? acc0 : acc1;
;             const f32x4 gj = *(const f32x4*)(GI + 16 * n + 4 * fq); const int i = 16 * m + fr, j0 = 16 * n + 4 * fq; float p[4];
; #pragma unroll
;             for (int e = 0; e < 4; ++e) p[e] = (j0 + e <= i) ? acc[e] * __expf(gi_i - gj[e]) : 0.f;
;             u32x2 w; w.x = cvt_pk_bf16(p[0], p[1]); w.y = cvt_pk_bf16(p[2], p[3]); *(u32x2*)(P + (16 * m + fr) * LJ + j0) = w;
;         }
;         const float ei = __expf(gi_i);
; #pragma unroll
;         for (int vt = 0; vt < NVTW; ++vt) O[vt] = O[vt] * ei;
;     }
;     __syncthreads();
	v_mfma_f32_16x16x32_bf16 v[76:79], v[170:173], v[166:169], v[76:79]
	v_mfma_f32_16x16x32_bf16 v[72:75], v[174:177], v[166:169], v[72:75]
	v_mfma_f32_16x16x32_bf16 v[80:83], v[178:181], v[166:169], v[80:83]
	v_mfma_f32_16x16x32_bf16 v[84:87], v[182:185], v[166:169], v[84:87]
	ds_read_b128 v[166:169], v126 offset:320
	ds_read_b128 v[170:173], v127 offset:34112
	ds_read_b128 v[174:177], v127 offset:42560
	ds_read_b128 v[178:181], v165 offset:320
	ds_read_b128 v[182:185], v165 offset:8768
	s_waitcnt lgkmcnt(5)
	v_mfma_f32_16x16x32_bf16 v[76:79], v[218:221], v[214:217], v[76:79]
	v_mfma_f32_16x16x32_bf16 v[72:75], v[222:225], v[214:217], v[72:75]
	v_mfma_f32_16x16x32_bf16 v[80:83], v[226:229], v[214:217], v[80:83]
	v_mfma_f32_16x16x32_bf16 v[84:87], v[230:233], v[214:217], v[84:87]
	ds_read_b128 v[214:217], v126 offset:384
	ds_read_b128 v[218:221], v127 offset:34176
	ds_read_b128 v[222:225], v127 offset:42624
	ds_read_b128 v[226:229], v165 offset:384
	ds_read_b128 v[230:233], v165 offset:8832
	s_waitcnt lgkmcnt(5)
	v_mfma_f32_16x16x32_bf16 v[76:79], v[170:173], v[166:169], v[76:79]
	v_mfma_f32_16x16x32_bf16 v[72:75], v[174:177], v[166:169], v[72:75]
	v_mfma_f32_16x16x32_bf16 v[80:83], v[178:181], v[166:169], v[80:83]
	v_mfma_f32_16x16x32_bf16 v[84:87], v[182:185], v[166:169], v[84:87]
	ds_read_b128 v[166:169], v126 offset:448
	ds_read_b128 v[170:173], v127 offset:34240
	ds_read_b128 v[174:177], v127 offset:42688
	ds_read_b128 v[178:181], v165 offset:448
	ds_read_b128 v[182:185], v165 offset:8896
	s_waitcnt lgkmcnt(5)
	v_mfma_f32_16x16x32_bf16 v[76:79], v[218:221], v[214:217], v[76:79]
	v_mfma_f32_16x16x32_bf16 v[72:75], v[222:225], v[214:217], v[72:75]
	v_mfma_f32_16x16x32_bf16 v[80:83], v[226:229], v[214:217], v[80:83]
	v_mfma_f32_16x16x32_bf16 v[84:87], v[230:233], v[214:217], v[84:87]
	s_waitcnt lgkmcnt(0)
	v_mfma_f32_16x16x32_bf16 v[76:79], v[170:173], v[166:169], v[76:79]
	v_mfma_f32_16x16x32_bf16 v[72:75], v[174:177], v[166:169], v[72:75]
	v_mfma_f32_16x16x32_bf16 v[80:83], v[178:181], v[166:169], v[80:83]
	v_mfma_f32_16x16x32_bf16 v[84:87], v[182:185], v[166:169], v[84:87]
	s_nop 7
	v_cmp_gt_i32_e32 vcc, s89, v132
	ds_read_b128 v[88:91], v128
	s_waitcnt lgkmcnt(0)
	v_sub_f32_e32 v16, v92, v88
	v_mul_f32_e32 v16, 0x3fb8aa3b, v16
	v_exp_f32_e32 v16, v16
	v_sub_f32_e32 v18, v92, v89
	v_sub_f32_e32 v19, v92, v90
	v_mul_f32_e32 v18, 0x3fb8aa3b, v18
	v_mul_f32_e32 v16, v76, v16
	v_mul_f32_e32 v19, 0x3fb8aa3b, v19
	v_sub_f32_e32 v76, v92, v91
	v_exp_f32_e32 v18, v18
	v_exp_f32_e32 v19, v19
	v_mul_f32_e32 v76, 0x3fb8aa3b, v76
	v_exp_f32_e32 v76, v76
	v_mul_f32_e32 v18, v77, v18
	v_mul_f32_e32 v19, v78, v19
	v_cndmask_b32_e64 v18, 0, v18, s[50:51]
	v_cndmask_b32_e64 v19, v19, 0, s[52:53]
	v_mul_f32_e32 v76, v79, v76
	v_cndmask_b32_e64 v16, v16, 0, s[48:49]
	v_cndmask_b32_e64 v76, v76, 0, s[54:55]
	v_cvt_pk_bf16_f32 v18, v16, v18
	v_cvt_pk_bf16_f32 v19, v19, v76
	ds_write_b64 v129, v[18:19]
	ds_read_b128 v[76:79], v128 offset:64
	s_waitcnt lgkmcnt(0)
	v_sub_f32_e32 v16, v92, v76
	v_mul_f32_e32 v16, 0x3fb8aa3b, v16
	v_sub_f32_e32 v18, v92, v77
	v_exp_f32_e32 v16, v16
	v_mul_f32_e32 v18, 0x3fb8aa3b, v18
	v_exp_f32_e32 v18, v18
	v_sub_f32_e32 v19, v92, v78
	v_mul_f32_e32 v16, v72, v16
	v_sub_f32_e32 v72, v92, v79
	v_mul_f32_e32 v18, v73, v18
	v_mul_f32_e32 v19, 0x3fb8aa3b, v19
	v_mul_f32_e32 v72, 0x3fb8aa3b, v72
	v_cndmask_b32_e64 v16, v16, 0, s[56:57]
	v_cndmask_b32_e64 v18, 0, v18, s[58:59]
	v_exp_f32_e32 v19, v19
	v_exp_f32_e32 v72, v72
	v_cvt_pk_bf16_f32 v18, v16, v18
	v_mul_f32_e32 v16, 0x3fb8aa3b, v92
	v_exp_f32_e32 v16, v16
	v_mul_f32_e32 v19, v74, v19
	v_mul_f32_e32 v72, v75, v72
	v_cndmask_b32_e64 v19, v19, 0, s[60:61]
	v_cndmask_b32_e64 v72, v72, 0, s[62:63]
	v_cvt_pk_bf16_f32 v19, v19, v72
	ds_write_b64 v129, v[18:19] offset:32
	v_pk_mul_f32 v[72:73], v[16:17], v[80:81] op_sel_hi:[0,1]
	v_pk_mul_f32 v[74:75], v[16:17], v[82:83] op_sel_hi:[0,1]
	v_pk_mul_f32 v[76:77], v[16:17], v[84:85] op_sel_hi:[0,1]
	v_pk_mul_f32 v[78:79], v[16:17], v[86:87] op_sel_hi:[0,1]
	s_waitcnt lgkmcnt(0)
	s_barrier
; __device__ __forceinline__ unsigned cvt_pk_bf16(float lo, float hi) { unsigned r; asm("v_cvt_pk_bf16_f32 %0, %1, %2" : "=v"(r) : "v"(lo), "v"(hi)); return r; }
; template <int DK, int DV, bool SEPQ> ...
;     ...
; #pragma unroll
;     for (int ks = 0; ks < 2; ++ks) { const bf16x8 pf = *(const bf16x8*)(P + (16 * m + fr) * LJ + 32 * ks + 8 * fq);
; #pragma unroll
;         for (int vt = 0; vt < NVTW; ++vt) { const bf16x8 vf = *(const bf16x8*)(VT + (16 * (hw * NVTW + vt) + fr) * LJ + 32 * ks + 8 * fq); O[vt] = __builtin_amdgcn_mfma_f32_16x16x32_bf16(vf, pf, O[vt], 0, 0, 0); } }
; #pragma unroll
;     for (int ct = 0; ct < NCTW; ++ct) { const int ctg = wid * NCTW + ct; const f32x4 dec = *(const f32x4*)(SDEC + 16 * ctg + 4 * fq);
; #pragma unroll
;         for (int vt = 0; vt < NVT; ++vt) S[ct][vt] = S[ct][vt] * dec;
; #pragma unroll
;         for (int ks = 0; ks < 2; ++ks) { const bf16x8 kf = *(const bf16x8*)(KT + (16 * ctg + fr) * LJ + 32 * ks + 8 * fq);
; #pragma unroll
;             for (int vt = 0; vt < NVT; ++vt) { const bf16x8 vf = *(const bf16x8*)(VT2 + (16 * vt + fr) * LJ + 32 * ks + 8 * fq); S[ct][vt] = __builtin_amdgcn_mfma_f32_16x16x32_bf16(kf, vf, S[ct][vt], 0, 0, 0); } } }
; __device__ __forceinline__ void ret_block(ArgsP a_, unsigned char* smem) { const ArgsP a = a_;
;     ...
;         const int m = wid >> 1, hw = wid & 1, i = 16 * m + fr;
;         if (i < len) {
; #pragma unroll
;             for (int vt = 0; vt < 2; ++vt) *(u32x2*)(OB + (size_t)(row0 + i) * 2048 + h * 512 + vs * 64 + 16 * (hw * 2 + vt) + 4 * fq) = (u32x2){cvt_pk_bf16(O[vt][0], O[vt][1]), cvt_pk_bf16(O[vt][2], O[vt][3])}; }
	ds_read_b128 v[214:217], v130
	ds_read_b128 v[218:221], v144
	ds_read_b128 v[222:225], v144 offset:2304
	ds_read_b128 v[226:229], v130 offset:64
	ds_read_b128 v[230:233], v144 offset:64
	ds_read_b128 v[234:237], v144 offset:2368
	ds_read_b128 v[238:241], v131
	ds_read_b128 v[242:245], v145
	ds_read_b128 v[246:249], v147
	ds_read_b128 v[166:169], v147 offset:2304
	ds_read_b128 v[170:173], v147 offset:4608
	ds_read_b128 v[174:177], v147 offset:6912
	ds_read_b128 v[178:181], v145 offset:64
	ds_read_b128 v[182:185], v147 offset:64
	ds_read_b128 v[80:83], v147 offset:2368
	s_waitcnt lgkmcnt(13)
	v_mfma_f32_16x16x32_bf16 v[72:75], v[218:221], v[214:217], v[72:75]
	ds_read_b128 v[84:87], v147 offset:4672
	ds_read_b128 v[88:91], v147 offset:6976
	s_waitcnt lgkmcnt(14)
	v_mfma_f32_16x16x32_bf16 v[76:79], v[222:225], v[214:217], v[76:79]
	ds_read_b128 v[218:221], v131 offset:64
	s_waitcnt lgkmcnt(13)
	v_mfma_f32_16x16x32_bf16 v[72:75], v[230:233], v[226:229], v[72:75]
	ds_read_b128 v[214:217], v164
	ds_read_b128 v[222:225], v164 offset:64
	s_waitcnt lgkmcnt(14)
	v_mfma_f32_16x16x32_bf16 v[76:79], v[234:237], v[226:229], v[76:79]
	s_waitcnt lgkmcnt(13)
	v_pk_mul_f32 v[42:43], v[42:43], v[240:241]
	v_pk_mul_f32 v[40:41], v[40:41], v[238:239]
	v_pk_mul_f32 v[46:47], v[46:47], v[240:241]
	v_pk_mul_f32 v[44:45], v[44:45], v[238:239]
	v_pk_mul_f32 v[50:51], v[50:51], v[240:241]
	v_pk_mul_f32 v[48:49], v[48:49], v[238:239]
	v_pk_mul_f32 v[54:55], v[54:55], v[240:241]
	v_pk_mul_f32 v[52:53], v[52:53], v[238:239]
	s_waitcnt lgkmcnt(11)
	v_mfma_f32_16x16x32_bf16 v[40:43], v[242:245], v[246:249], v[40:43]
	s_waitcnt lgkmcnt(10)
	v_mfma_f32_16x16x32_bf16 v[44:47], v[242:245], v[166:169], v[44:47]
	s_waitcnt lgkmcnt(9)
	v_mfma_f32_16x16x32_bf16 v[48:51], v[242:245], v[170:173], v[48:51]
	s_waitcnt lgkmcnt(8)
	v_mfma_f32_16x16x32_bf16 v[52:55], v[242:245], v[174:177], v[52:55]
	s_waitcnt lgkmcnt(6)
	v_mfma_f32_16x16x32_bf16 v[40:43], v[178:181], v[182:185], v[40:43]
	s_waitcnt lgkmcnt(5)
	v_mfma_f32_16x16x32_bf16 v[44:47], v[178:181], v[80:83], v[44:47]
	s_waitcnt lgkmcnt(4)
	v_mfma_f32_16x16x32_bf16 v[48:51], v[178:181], v[84:87], v[48:51]
	s_waitcnt lgkmcnt(3)
	v_mfma_f32_16x16x32_bf16 v[52:55], v[178:181], v[88:91], v[52:55]
	s_waitcnt lgkmcnt(2)
	v_pk_mul_f32 v[58:59], v[58:59], v[220:221]
	v_pk_mul_f32 v[56:57], v[56:57], v[218:219]
	v_pk_mul_f32 v[62:63], v[62:63], v[220:221]
	v_pk_mul_f32 v[60:61], v[60:61], v[218:219]
	v_pk_mul_f32 v[66:67], v[66:67], v[220:221]
	v_pk_mul_f32 v[64:65], v[64:65], v[218:219]
	v_pk_mul_f32 v[70:71], v[70:71], v[220:221]
	v_pk_mul_f32 v[68:69], v[68:69], v[218:219]
	s_waitcnt lgkmcnt(1)
	v_mfma_f32_16x16x32_bf16 v[56:59], v[214:217], v[246:249], v[56:59]
	v_mfma_f32_16x16x32_bf16 v[60:63], v[214:217], v[166:169], v[60:63]
	v_mfma_f32_16x16x32_bf16 v[64:67], v[214:217], v[170:173], v[64:67]
	v_mfma_f32_16x16x32_bf16 v[68:71], v[214:217], v[174:177], v[68:71]
	s_waitcnt lgkmcnt(0)
	v_mfma_f32_16x16x32_bf16 v[56:59], v[222:225], v[182:185], v[56:59]
	v_mfma_f32_16x16x32_bf16 v[60:63], v[222:225], v[80:83], v[60:63]
	v_mfma_f32_16x16x32_bf16 v[64:67], v[222:225], v[84:87], v[64:67]
	v_mfma_f32_16x16x32_bf16 v[68:71], v[222:225], v[88:91], v[68:71]
	s_waitcnt vmcnt(0)
	s_and_saveexec_b64 s[64:65], vcc
	s_cbranch_execz .LBB0_303
	v_add_u32_e32 v18, s88, v132
	v_ashrrev_i32_e32 v19, 31, v18
	v_lshlrev_b64 v[18:19], 12, v[18:19]
	v_lshl_add_u64 v[18:19], s[26:27], 0, v[18:19]
	s_lshl_b32 s70, s91, 10
	s_mov_b32 s71, s12
	v_lshl_add_u64 v[18:19], v[18:19], 0, s[70:71]
	s_lshl_b32 s70, s90, 7
	v_lshl_add_u64 v[18:19], v[18:19], 0, s[70:71]
	v_mov_b32_e32 v113, v17
	v_lshl_add_u64 v[18:19], v[18:19], 0, v[112:113]
	v_mov_b32_e32 v115, v17
	v_cvt_pk_bf16_f32 v72, v72, v73
	v_cvt_pk_bf16_f32 v73, v74, v75
	v_lshl_add_u64 v[18:19], v[18:19], 0, v[114:115]
	global_store_dwordx2 v[18:19], v[72:73], off
	v_cvt_pk_bf16_f32 v72, v76, v77
	v_cvt_pk_bf16_f32 v73, v78, v79
	global_store_dwordx2 v[18:19], v[72:73], off offset:32

; __device__ __forceinline__ int TID() { int t = threadIdx.x; asm volatile("" : "+v"(t)); return t; }
; __device__ __forceinline__ int BID() { int t = blockIdx.x; asm volatile("" : "+s"(t)); return t; }
; __device__ __forceinline__ void mamba_block(ArgsP a_, unsigned char* smem) { const ArgsP a = a_;
;     ...
;     const int tid = TID(), wid = tid >> 6, lane = tid & 63, fr = lane & 15, fq = lane >> 4;
;     const int G = gridDim.x, cb0 = BID();
;     const int cb = (G == 256) ? ((((cb0 & 7) * 8 + (cb0 >> 5)) << 2) | ((cb0 >> 3) & 3)) : cb0;
;     const unsigned char* proj = a->ws + B_PROJ;
;     const bf16_t* ZG = (const bf16_t*)proj; const float* DT = (const float*)(proj + (size_t)MP * 12288); const bf16_t* XC = (const bf16_t*)(proj + (size_t)MP * 13312);
;     bf16_t* YB = (bf16_t*)(a->ws + B_PART);
;     const int np = cb < 256 ? 33 : 0; const int nsmp = (4096 - (cb % 256) + G - 1) / G; const int nunits = np + nsmp;
;     f32x4 S[1][4]; f32x4 O[2];
;     u32x4 bpre[2], cpre[2]; bf16_t xpre[8]; float dtpre = 0.f;
;     const int vv = tid & 63, jg = tid >> 6;
;     ...
;     if (nunits > 0) MB_LOAD(0);
;     const int ntot_ = np + nsmp * REP_SMP;
.LBB0_322:
	s_add_u32 s24, s26, 0x208e0000
	s_addc_u32 s25, s27, 0
	s_add_u32 s26, s26, 0x17ee0000
	s_addc_u32 s27, s27, 0
	s_ashr_i32 s22, s18, 5
	v_lshrrev_b32_e32 v22, 4, v18
	v_writelane_b32 v255, s22, 14
	s_mulk_i32 s22, 0x810
	v_writelane_b32 v255, s22, 4
	v_lshlrev_b32_e32 v23, 4, v19
	v_lshlrev_b32_e32 v24, 2, v22
	v_lshlrev_b32_e32 v25, 2, v57
	s_add_i32 s22, 0, 0x18000
	v_readlane_b32 s64, v254, 33
	v_readlane_b32 s66, v254, 34
	v_or_b32_e32 v20, v24, v23
	v_lshlrev_b32_e32 v16, 4, v57
	v_add_u32_e32 v69, s22, v25
	v_add_u32_e32 v76, s64, v25
	v_add_u32_e32 v77, s66, v25
	v_mul_u32_u24_e32 v25, 0x48, v18
	v_readlane_b32 s34, v255, 12
	v_ashrrev_i32_e32 v21, 31, v20
	v_and_b32_e32 v16, 0xf0, v16
	v_lshl_add_u32 v25, v25, 1, 0
	s_movk_i32 s23, 0xff74
	v_readlane_b32 s35, v255, 13
	v_lshlrev_b64 v[58:59], 8, v[20:21]
	v_add_u32_e32 v20, 0, v16
	v_add_u32_e32 v79, v25, v23
	v_mad_i32_i24 v25, v18, s23, v25
	v_mul_u32_u24_e32 v26, 0x11c, v18
	v_lshl_add_u64 v[60:61], s[34:35], 0, v[16:17]
	v_lshlrev_b32_e32 v16, 1, v18
	v_add3_u32 v80, v25, v26, v23
	v_lshl_add_u64 v[62:63], s[34:35], 0, v[16:17]
	v_lshlrev_b32_e32 v26, 5, v19
	v_lshlrev_b32_e32 v16, 3, v22
	v_readlane_b32 s23, v254, 35
	v_lshlrev_b32_e32 v29, 1, v19
	v_and_b32_e32 v56, 15, v57
	v_add3_u32 v22, s23, v26, v16
	v_ashrrev_i32_e32 v16, 7, v57
	v_and_b32_e32 v29, 2, v29
	v_and_b32_e32 v30, 48, v18
	v_lshl_or_b32 v28, v16, 4, v56
	v_cmp_le_i32_e64 s[42:43], v29, v16
	v_cmp_ge_i32_e64 s[44:45], v29, v16
	v_add_u32_e32 v16, 0, v30
	s_movk_i32 s67, 0x110
	v_mad_u64_u32 v[64:65], s[34:35], v28, s67, v[16:17]
	v_add_u32_e32 v31, s23, v30
	s_movk_i32 s23, 0x90
	v_lshlrev_b32_e32 v32, 4, v29
	v_mul_lo_u32 v35, v28, s23
	v_readlane_b32 s34, v254, 36
	v_or_b32_e32 v23, v23, v56
	v_lshlrev_b32_e32 v21, 3, v57
	v_or_b32_e32 v33, v32, v56
	v_add_u32_e32 v35, s34, v35
	v_or_b32_e32 v66, v32, v24
	v_mad_u64_u32 v[70:71], s[34:35], v23, s23, v[16:17]
	v_ashrrev_i32_e32 v32, 3, v57
	v_ashrrev_i32_e32 v85, 4, v57
	v_lshlrev_b32_e32 v78, 3, v19
	v_bfi_b32 v71, -16, v32, v57
	v_mad_u64_u32 v[72:73], s[34:35], v85, s67, v[20:21]
	v_add_u32_e32 v32, 0x200, v57
	v_or_b32_e32 v24, 2, v66
	v_ashrrev_i32_e32 v73, 4, v32
	v_or_b32_e32 v88, 2, v78
	v_cmp_gt_i32_e64 s[50:51], v24, v28
	v_or_b32_e32 v24, 3, v66
	v_mad_u64_u32 v[74:75], s[34:35], v73, s67, v[20:21]
	v_lshlrev_b32_e32 v20, 2, v88
	v_or_b32_e32 v92, 4, v78
	v_lshlrev_b32_e32 v29, 6, v29
	v_cmp_gt_i32_e64 s[52:53], v24, v28
	v_or_b32_e32 v24, 18, v66
	v_add_u32_e32 v89, s64, v20
	v_add_u32_e32 v91, s66, v20
	v_lshlrev_b32_e32 v20, 2, v92
	v_or_b32_e32 v96, 6, v78
	v_lshl_add_u32 v81, v28, 2, s22
	v_add3_u32 v82, s22, v30, v29
	v_or_b32_e32 v68, 16, v66
	v_cmp_gt_i32_e64 s[58:59], v24, v28
	v_or_b32_e32 v24, 19, v66
	v_add_u32_e32 v84, v35, v30
	v_readlane_b32 s22, v254, 37
	v_mov_b32_e32 v30, 0x1200
	v_add_u32_e32 v93, s64, v20
	v_add_u32_e32 v95, s66, v20
	v_lshlrev_b32_e32 v20, 2, v96
	s_abs_i32 s65, s65
	v_cmp_gt_i32_e64 s[46:47], v66, v28
	v_cmp_lt_i32_e64 s[48:49], v66, v28
	v_cmp_gt_i32_e64 s[54:55], v68, v28
	v_cmp_lt_i32_e64 s[56:57], v68, v28
	v_cmp_gt_i32_e64 s[60:61], v24, v28
	v_lshl_add_u32 v28, v19, 6, s22
	v_mad_u32_u24 v30, v56, s23, v30
	v_cmp_eq_u32_e64 s[22:23], 0, v18
	v_add_u32_e32 v97, s64, v20
	v_add_u32_e32 v99, s66, v20
	v_cvt_f32_u32_e32 v20, s65
	v_writelane_b32 v255, s22, 16
	v_add_u32_e32 v75, s64, v26
	v_add_u32_e32 v87, s66, v26
	v_writelane_b32 v255, s23, 17
	v_cmp_gt_u32_e64 s[22:23], 2, v18
	v_rcp_iflag_f32_e32 v20, v20
	v_mul_u32_u24_e32 v27, 0x110, v56
	v_writelane_b32 v255, s22, 18
	v_mul_u32_u24_e32 v34, 0x110, v33
	v_mul_f32_e32 v20, 0x4f7ffffe, v20
	v_writelane_b32 v255, s23, 19
	v_cmp_gt_u32_e64 s[22:23], 4, v18
	v_cvt_u32_f32_e32 v20, v20
	v_mul_u32_u24_e32 v24, 0x90, v33
	v_writelane_b32 v255, s22, 20
	v_and_b32_e32 v29, 48, v57
	v_mul_u32_u24_e32 v23, 0x90, v56
	v_writelane_b32 v255, s23, 21
	v_cmp_gt_u32_e64 s[22:23], 8, v18
	v_cmp_gt_i32_e64 s[40:41], 64, v57
	v_mad_u32_u24 v65, v33, s67, v16
	v_writelane_b32 v255, s22, 22
	v_lshl_add_u32 v83, v66, 1, v35
	s_mov_b32 s34, 0
	v_writelane_b32 v255, s23, 23
	v_cmp_gt_u32_e64 s[22:23], 16, v18
	v_or_b32_e32 v86, 1, v78
	v_or_b32_e32 v90, 3, v78
	v_writelane_b32 v255, s22, 24
	v_or_b32_e32 v94, 5, v78
	v_or_b32_e32 v98, 7, v78
	v_writelane_b32 v255, s23, 25
	v_cmp_gt_u32_e64 s[22:23], 32, v18
	v_lshlrev_b32_e32 v18, 2, v18
	v_add_u32_e32 v109, v22, v27
	v_writelane_b32 v255, s22, 26
	v_add_u32_e32 v110, v16, v24
	v_add_u32_e32 v111, v28, v29
	v_writelane_b32 v255, s23, 27
	s_movk_i32 s22, 0x880
	v_mul_lo_u32 v19, v19, s22
	s_sub_i32 s22, 0, s65
	v_readfirstlane_b32 s23, v20
	v_add_u32_e32 v100, v25, v19
	v_add3_u32 v101, 0, v19, v18
	v_mul_lo_u32 v19, v88, s67
	s_mul_i32 s22, s22, s23
	v_add_u32_e32 v102, v25, v19
	v_add3_u32 v103, 0, v19, v18
	v_add_u32_e32 v26, 0x220, v19
	v_add_u32_e32 v19, 0x440, v19
	s_mul_hi_u32 s22, s23, s22
	v_add3_u32 v105, 0, v26, v18
	v_add3_u32 v107, 0, v19, v18
	s_add_i32 s66, s23, s22
	s_sub_i32 s22, s68, s69
	v_mov_b32_e32 v20, 0
	v_add_u32_e32 v18, 0, v21
	v_add_u32_e32 v104, v25, v26
	v_add_u32_e32 v106, v25, v19
	s_sub_i32 s67, 0, s19
	s_sub_i32 s68, s22, s19
	v_add_u32_e32 v108, 0x18100, v18
	v_add_u32_e32 v112, v16, v23
	v_add_u32_e32 v113, v16, v30
	v_add_u32_e32 v114, v31, v34
	v_mov_b32_e32 v21, v20
	v_mov_b32_e32 v22, v20
	v_mov_b32_e32 v23, v20
	v_mov_b32_e32 v24, v20
	v_mov_b32_e32 v25, v20
	v_mov_b32_e32 v26, v20
	v_mov_b32_e32 v27, v20
	v_mov_b32_e32 v28, v20
	v_mov_b32_e32 v29, v20
	v_mov_b32_e32 v30, v20
	v_mov_b32_e32 v31, v20
	v_mov_b32_e32 v32, v20
	v_mov_b32_e32 v33, v20
	v_mov_b32_e32 v34, v20
	v_mov_b32_e32 v35, v20
	s_waitcnt vmcnt(0)
	s_branch .LBB0_324

.LBB0_333:
	s_cmp_eq_u32 s73, 64
	s_cbranch_scc1 .Lmb_mask_done
	v_cmp_gt_i32_e32 vcc, s73, v85
	s_nop 1
	v_cndmask_b32_e32 v3, 0, v3, vcc
	v_cndmask_b32_e32 v2, 0, v2, vcc
	v_cndmask_b32_e32 v1, 0, v1, vcc
	v_cndmask_b32_e32 v0, 0, v0, vcc
	v_cndmask_b32_e32 v7, 0, v7, vcc
	v_cndmask_b32_e32 v6, 0, v6, vcc
	v_cndmask_b32_e32 v5, 0, v5, vcc
	v_cndmask_b32_e32 v4, 0, v4, vcc
	v_cmp_gt_i32_e32 vcc, s73, v73
	s_nop 1
	v_cndmask_b32_e32 v11, 0, v11, vcc
	v_cndmask_b32_e32 v10, 0, v10, vcc
	v_cndmask_b32_e32 v9, 0, v9, vcc
	v_cndmask_b32_e32 v8, 0, v8, vcc
	v_cndmask_b32_e32 v15, 0, v15, vcc
	v_cndmask_b32_e32 v14, 0, v14, vcc
	v_cndmask_b32_e32 v13, 0, v13, vcc
	v_cndmask_b32_e32 v12, 0, v12, vcc
	v_cmp_gt_i32_e32 vcc, s73, v78
	s_nop 1
	v_cndmask_b32_e32 v115, 0, v115, vcc
	v_cmp_gt_i32_e32 vcc, s73, v86
	s_nop 1
	v_cndmask_b32_e32 v116, 0, v116, vcc
	v_cmp_gt_i32_e32 vcc, s73, v88
	s_nop 1
	v_cndmask_b32_e32 v117, 0, v117, vcc
	v_cmp_gt_i32_e32 vcc, s73, v90
	s_nop 1
	v_cndmask_b32_e32 v120, 0, v120, vcc
	v_cmp_gt_i32_e32 vcc, s73, v92
	s_nop 1
	v_cndmask_b32_e32 v118, 0, v118, vcc
	v_cmp_gt_i32_e32 vcc, s73, v94
	s_nop 1
	v_cndmask_b32_e32 v119, 0, v119, vcc
	v_cmp_gt_i32_e32 vcc, s73, v96
	s_nop 1
	v_cndmask_b32_e32 v121, 0, v121, vcc
	v_cmp_gt_i32_e32 vcc, s73, v98
	s_nop 1
	v_cndmask_b32_e32 v122, 0, v122, vcc

; __device__ __forceinline__ unsigned cvt_pk_bf16(float lo, float hi) { unsigned r; asm("v_cvt_pk_bf16_f32 %0, %1, %2" : "=v"(r) : "v"(lo), "v"(hi)); return r; }
; template <int DK, int DV, bool SEPQ> ...
;     ...
;         for (int vt = 0; vt < NVT; ++vt) { const f32x4 s = S[ct][vt]; u32x2 w; w.x = cvt_pk_bf16(s[0], s[1]); w.y = cvt_pk_bf16(s[2], s[3]);
;             *(u32x2*)(ST + (16 * vt + fr) * LQ + 16 * (wid * NCTW + ct) + 4 * fq) = w; }
;     __syncthreads();
; __device__ __forceinline__ void mamba_block(ArgsP a_, unsigned char* smem) { const ArgsP a = a_;
;     ...
;             const float glast = __shfl(x, 63); GI[j] = x; DTV[j] = dt; W2[j] = dt * __expf(glast - x); const float ed = __expf(glast); SDEC[2 * j] = ed; SDEC[2 * j + 1] = ed; }
.LBB0_348:
	s_or_b64 exec, exec, s[74:75]
	s_cmp_lg_u32 s73, 8
	s_cbranch_scc1 .Lmb_st_nowait
	s_waitcnt vmcnt(0)
.Lmb_st_nowait:
	v_cvt_pk_bf16_f32 v36, v20, v21
	v_cvt_pk_bf16_f32 v37, v22, v23
	ds_write_b64 v109, v[36:37]
	v_cvt_pk_bf16_f32 v36, v24, v25
	v_cvt_pk_bf16_f32 v37, v26, v27
	ds_write_b64 v109, v[36:37] offset:4352
	v_cvt_pk_bf16_f32 v36, v28, v29
	v_cvt_pk_bf16_f32 v37, v30, v31
	ds_write_b64 v109, v[36:37] offset:8704
	v_cvt_pk_bf16_f32 v36, v32, v33
	v_cvt_pk_bf16_f32 v37, v34, v35
	ds_write_b64 v109, v[36:37] offset:13056
	s_waitcnt lgkmcnt(0)
	s_barrier
	s_mov_b64 s[74:75], exec
	v_cmp_gt_u32_e32 vcc, 64, v186
	s_and_b64 exec, exec, vcc
	s_cbranch_execz .Lmb_sdec_skip
	ds_write_b64 v108, v[18:19]

; template <int DK, int DV, bool SEPQ> ...
;     ...
;         const float gi_i = GI[16 * m + fr];
;         const int n0 = 2 * hw, n1 = 2 * hw + 1; const bool do0 = n0 <= m, do1 = n1 <= m;
;         f32x4 acc0 = {0.f, 0.f, 0.f, 0.f}, acc1 = {0.f, 0.f, 0.f, 0.f};
; #pragma unroll
;         for (int vt = 0; vt < NVTW; ++vt) O[vt] = (f32x4){0.f, 0.f, 0.f, 0.f};
; #pragma unroll
;         for (int ks = 0; ks < DK / 32; ++ks) {
;             const bf16x8 qf = *(const bf16x8*)(QA + (16 * m + fr) * LQ + 32 * ks + 8 * fq);
;             if (do0) { const bf16x8 kf = *(const bf16x8*)(KB + (16 * n0 + fr) * LQ + 32 * ks + 8 * fq); acc0 = __builtin_amdgcn_mfma_f32_16x16x32_bf16(kf, qf, acc0, 0, 0, 0); }
;             if (do1) { const bf16x8 kf = *(const bf16x8*)(KB + (16 * n1 + fr) * LQ + 32 * ks + 8 * fq); acc1 = __builtin_amdgcn_mfma_f32_16x16x32_bf16(kf, qf, acc1, 0, 0, 0); }
;             bf16x8 qs = qf; if (SEPQ) qs = *(const bf16x8*)(QS + (16 * m + fr) * LQ + 32 * ks + 8 * fq);
; #pragma unroll
;             for (int vt = 0; vt < NVTW; ++vt) { const bf16x8 sf = *(const bf16x8*)(ST + (16 * (hw * NVTW + vt) + fr) * LQ + 32 * ks + 8 * fq); O[vt] = __builtin_amdgcn_mfma_f32_16x16x32_bf16(sf, qs, O[vt], 0, 0, 0); }
;         }
; #pragma unroll
;         for (int nn = 0; nn < 2; ++nn) {
;             const int n = 2 * hw + nn; const f32x4 acc = nn == 0 ? acc0 : acc1;
;             const f32x4 gj = *(const f32x4*)(GI + 16 * n + 4 * fq); const int i = 16 * m + fr, j0 = 16 * n + 4 * fq; float p[4];
; #pragma unroll
;             for (int e = 0; e < 4; ++e) p[e] = (j0 + e <= i) ? acc[e] * __expf(gi_i - gj[e]) : 0.f;
;             u32x2 w; w.x = cvt_pk_bf16(p[0], p[1]); w.y = cvt_pk_bf16(p[2], p[3]); *(u32x2*)(P + (16 * m + fr) * LJ + j0) = w;
;         }
;         const float ei = __expf(gi_i);
; #pragma unroll
;         for (int vt = 0; vt < NVTW; ++vt) O[vt] = O[vt] * ei;
; __device__ __forceinline__ void mamba_block(ArgsP a_, unsigned char* smem) { const ArgsP a = a_;
;     ...
;         if (i < len) { const float Dh = AIN(24)[hd];
; #pragma unroll
;             for (int vt = 0; vt < 2; ++vt) { const int v = 16 * (hw * 2 + vt) + 4 * fq; const size_t o = (size_t)(row0 + i) * 2048 + hd * 64 + v;
;                 const u32x2 xt = *(const u32x2*)(XC + (size_t)(row0 + i) * 4096 + hd * 64 + v); const u32x2 zt = *(const u32x2*)(ZG + o);
.LBB0_356:
	s_load_dwordx2 s[22:23], s[4:5], 0xc0
	v_add_u32_e32 v212, s72, v71
	v_ashrrev_i32_e32 v213, 31, v212
	v_lshlrev_b64 v[214:215], 11, v[212:213]
	v_lshlrev_b64 v[212:213], 13, v[212:213]
	v_readlane_b32 s74, v255, 12
	v_readlane_b32 s75, v255, 13
	v_lshl_or_b32 v216, s71, 6, v214
	v_or_b32_e32 v214, v216, v66
	s_nop 0
	v_lshl_add_u64 v[212:213], s[74:75], 0, v[212:213]
	s_lshl_b32 s74, s71, 7
	s_mov_b32 s75, s12
	v_lshl_add_u64 v[212:213], v[212:213], 0, s[74:75]
	v_lshlrev_b32_e32 v218, 1, v66
	v_mov_b32_e32 v219, 0
	v_lshl_add_u64 v[212:213], v[212:213], 0, v[218:219]
	v_lshlrev_b64 v[218:219], 1, v[214:215]
	global_load_dwordx2 v[202:203], v[212:213], off
	v_lshl_add_u64 v[218:219], s[24:25], 0, v[218:219]
	global_load_dwordx2 v[204:205], v[218:219], off
	global_load_dwordx2 v[206:207], v[212:213], off offset:32
	v_or_b32_e32 v214, v216, v68
	v_lshlrev_b64 v[218:219], 1, v[214:215]
	v_lshl_add_u64 v[218:219], s[24:25], 0, v[218:219]
	global_load_dwordx2 v[208:209], v[218:219], off
	s_lshl_b32 s74, s71, 2
	v_mov_b32_e32 v217, s74
	s_waitcnt lgkmcnt(0)
	global_load_dword v210, v217, s[22:23]
	s_waitcnt lgkmcnt(0)
	ds_read_b32 v123, v81
	ds_read_b128 v[220:223], v64
	ds_read_b128 v[224:227], v65 offset:17408
	ds_read_b128 v[228:231], v65 offset:21760
	ds_read_b128 v[232:235], v114
	ds_read_b128 v[236:239], v114 offset:4352
	ds_read_b128 v[164:167], v64 offset:64
	ds_read_b128 v[168:171], v65 offset:17472
	ds_read_b128 v[172:175], v65 offset:21824
	ds_read_b128 v[176:179], v114 offset:64
	ds_read_b128 v[180:183], v114 offset:4416
	s_waitcnt lgkmcnt(5)
	v_mfma_f32_16x16x32_bf16 v[40:43], v[224:227], v[220:223], 0
	v_mfma_f32_16x16x32_bf16 v[36:39], v[228:231], v[220:223], 0
	v_mfma_f32_16x16x32_bf16 v[44:47], v[232:235], v[220:223], 0
	v_mfma_f32_16x16x32_bf16 v[48:51], v[236:239], v[220:223], 0
	ds_read_b128 v[220:223], v64 offset:128
	ds_read_b128 v[224:227], v65 offset:17536
	ds_read_b128 v[228:231], v65 offset:21888
	ds_read_b128 v[232:235], v114 offset:128
	ds_read_b128 v[236:239], v114 offset:4480
	s_waitcnt lgkmcnt(5)
	v_mfma_f32_16x16x32_bf16 v[40:43], v[168:171], v[164:167], v[40:43]
	v_mfma_f32_16x16x32_bf16 v[36:39], v[172:175], v[164:167], v[36:39]
	v_mfma_f32_16x16x32_bf16 v[44:47], v[176:179], v[164:167], v[44:47]
	v_mfma_f32_16x16x32_bf16 v[48:51], v[180:183], v[164:167], v[48:51]
	ds_read_b128 v[164:167], v64 offset:192
	ds_read_b128 v[168:171], v65 offset:17600
	ds_read_b128 v[172:175], v65 offset:21952
	ds_read_b128 v[176:179], v114 offset:192
	ds_read_b128 v[180:183], v114 offset:4544
	s_waitcnt lgkmcnt(5)
	v_mfma_f32_16x16x32_bf16 v[40:43], v[224:227], v[220:223], v[40:43]
	v_mfma_f32_16x16x32_bf16 v[36:39], v[228:231], v[220:223], v[36:39]
	v_mfma_f32_16x16x32_bf16 v[44:47], v[232:235], v[220:223], v[44:47]
	v_mfma_f32_16x16x32_bf16 v[48:51], v[236:239], v[220:223], v[48:51]
	s_waitcnt lgkmcnt(0)
	v_mfma_f32_16x16x32_bf16 v[40:43], v[168:171], v[164:167], v[40:43]
	v_mfma_f32_16x16x32_bf16 v[36:39], v[172:175], v[164:167], v[36:39]
	v_mfma_f32_16x16x32_bf16 v[44:47], v[176:179], v[164:167], v[44:47]
	v_mfma_f32_16x16x32_bf16 v[48:51], v[180:183], v[164:167], v[48:51]
	s_nop 7
	v_cmp_gt_i32_e32 vcc, s73, v71
	ds_read_b128 v[52:55], v82
	s_waitcnt lgkmcnt(0)
	v_sub_f32_e32 v16, v123, v52
	v_mul_f32_e32 v16, 0x3fb8aa3b, v16
	v_exp_f32_e32 v16, v16
	v_sub_f32_e32 v18, v123, v53
	v_sub_f32_e32 v19, v123, v54
	v_mul_f32_e32 v18, 0x3fb8aa3b, v18
	v_mul_f32_e32 v16, v40, v16
	v_mul_f32_e32 v19, 0x3fb8aa3b, v19
	v_sub_f32_e32 v40, v123, v55
	v_exp_f32_e32 v18, v18
	v_exp_f32_e32 v19, v19
	v_mul_f32_e32 v40, 0x3fb8aa3b, v40
	v_exp_f32_e32 v40, v40
	v_mul_f32_e32 v18, v41, v18
	v_mul_f32_e32 v19, v42, v19
	v_cndmask_b32_e64 v18, 0, v18, s[48:49]
	v_cndmask_b32_e64 v19, v19, 0, s[50:51]
	v_mul_f32_e32 v40, v43, v40
	v_cndmask_b32_e64 v16, v16, 0, s[46:47]
	v_cndmask_b32_e64 v40, v40, 0, s[52:53]
	v_cvt_pk_bf16_f32 v18, v16, v18
	v_cvt_pk_bf16_f32 v19, v19, v40
	ds_write_b64 v83, v[18:19]
	ds_read_b128 v[40:43], v82 offset:64
	s_waitcnt lgkmcnt(0)
	v_sub_f32_e32 v16, v123, v40
	v_mul_f32_e32 v16, 0x3fb8aa3b, v16
	v_sub_f32_e32 v18, v123, v41
	v_exp_f32_e32 v16, v16
	v_mul_f32_e32 v18, 0x3fb8aa3b, v18
	v_exp_f32_e32 v18, v18
	v_sub_f32_e32 v19, v123, v42
	v_mul_f32_e32 v16, v36, v16
	v_sub_f32_e32 v36, v123, v43
	v_mul_f32_e32 v18, v37, v18
	v_mul_f32_e32 v19, 0x3fb8aa3b, v19
	v_mul_f32_e32 v36, 0x3fb8aa3b, v36
	v_cndmask_b32_e64 v16, v16, 0, s[54:55]
	v_cndmask_b32_e64 v18, 0, v18, s[56:57]
	v_exp_f32_e32 v19, v19
	v_exp_f32_e32 v36, v36
	v_cvt_pk_bf16_f32 v18, v16, v18
	v_mul_f32_e32 v16, 0x3fb8aa3b, v123
	v_exp_f32_e32 v16, v16
	v_mul_f32_e32 v19, v38, v19
	v_mul_f32_e32 v36, v39, v36
	v_cndmask_b32_e64 v19, v19, 0, s[58:59]
	v_cndmask_b32_e64 v36, v36, 0, s[60:61]
	v_cvt_pk_bf16_f32 v19, v19, v36
	ds_write_b64 v83, v[18:19] offset:32
	v_pk_mul_f32 v[36:37], v[16:17], v[44:45] op_sel_hi:[0,1]
	v_pk_mul_f32 v[38:39], v[16:17], v[46:47] op_sel_hi:[0,1]
	v_pk_mul_f32 v[40:41], v[16:17], v[48:49] op_sel_hi:[0,1]
	v_pk_mul_f32 v[42:43], v[16:17], v[50:51] op_sel_hi:[0,1]
	s_waitcnt lgkmcnt(0)
	s_barrier
; __device__ __forceinline__ unsigned cvt_pk_bf16(float lo, float hi) { unsigned r; asm("v_cvt_pk_bf16_f32 %0, %1, %2" : "=v"(r) : "v"(lo), "v"(hi)); return r; }
; template <int DK, int DV, bool SEPQ> ...
;     ...
; #pragma unroll
;     for (int ks = 0; ks < 2; ++ks) { const bf16x8 pf = *(const bf16x8*)(P + (16 * m + fr) * LJ + 32 * ks + 8 * fq);
; #pragma unroll
;         for (int vt = 0; vt < NVTW; ++vt) { const bf16x8 vf = *(const bf16x8*)(VT + (16 * (hw * NVTW + vt) + fr) * LJ + 32 * ks + 8 * fq); O[vt] = __builtin_amdgcn_mfma_f32_16x16x32_bf16(vf, pf, O[vt], 0, 0, 0); } }
; #pragma unroll
;     for (int ct = 0; ct < NCTW; ++ct) { const int ctg = wid * NCTW + ct; const f32x4 dec = *(const f32x4*)(SDEC + 16 * ctg + 4 * fq);
; #pragma unroll
;         for (int vt = 0; vt < NVT; ++vt) S[ct][vt] = S[ct][vt] * dec;
; #pragma unroll
;         for (int ks = 0; ks < 2; ++ks) { const bf16x8 kf = *(const bf16x8*)(KT + (16 * ctg + fr) * LJ + 32 * ks + 8 * fq);
; #pragma unroll
;             for (int vt = 0; vt < NVT; ++vt) { const bf16x8 vf = *(const bf16x8*)(VT2 + (16 * vt + fr) * LJ + 32 * ks + 8 * fq); S[ct][vt] = __builtin_amdgcn_mfma_f32_16x16x32_bf16(kf, vf, S[ct][vt], 0, 0, 0); } } }
; __device__ __forceinline__ void mamba_block(ArgsP a_, unsigned char* smem) { const ArgsP a = a_;
;     ...
;         if (i < len) { const float Dh = AIN(24)[hd];
; #pragma unroll
;             for (int vt = 0; vt < 2; ++vt) { const int v = 16 * (hw * 2 + vt) + 4 * fq; const size_t o = (size_t)(row0 + i) * 2048 + hd * 64 + v;
;                 const u32x2 xt = *(const u32x2*)(XC + (size_t)(row0 + i) * 4096 + hd * 64 + v); const u32x2 zt = *(const u32x2*)(ZG + o);
;                 const f32x4 xs = {__uint_as_float(xt.x << 16), __uint_as_float(xt.x & 0xffff0000u), __uint_as_float(xt.y << 16), __uint_as_float(xt.y & 0xffff0000u)};
;                 const f32x4 zg = {__uint_as_float(zt.x << 16), __uint_as_float(zt.x & 0xffff0000u), __uint_as_float(zt.y << 16), __uint_as_float(zt.y & 0xffff0000u)};
;                 const f32x4 y = (O[vt] + xs * Dh) * zg; *(u32x2*)(YB + o) = (u32x2){cvt_pk_bf16(y[0], y[1]), cvt_pk_bf16(y[2], y[3])}; } }
	ds_read_b128 v[220:223], v84
	ds_read_b128 v[224:227], v110 offset:53248
	ds_read_b128 v[228:231], v110 offset:55552
	ds_read_b128 v[232:235], v84 offset:64
	ds_read_b128 v[236:239], v110 offset:53312
	ds_read_b128 v[240:243], v110 offset:55616
	ds_read_b128 v[244:247], v111
	ds_read_b128 v[248:251], v70 offset:34816
	ds_read_b128 v[164:167], v112 offset:62464
	ds_read_b128 v[168:171], v112 offset:64768
	ds_read_b128 v[172:175], v113 offset:62464
	ds_read_b128 v[176:179], v113 offset:64768
	ds_read_b128 v[180:183], v70 offset:34880
	s_waitcnt lgkmcnt(11)
	v_mfma_f32_16x16x32_bf16 v[36:39], v[224:227], v[220:223], v[36:39]
	ds_read_b128 v[224:227], v112 offset:62528
	s_waitcnt lgkmcnt(11)
	v_mfma_f32_16x16x32_bf16 v[44:47], v[228:231], v[220:223], v[40:43]
	ds_read_b128 v[220:223], v112 offset:64832
	ds_read_b128 v[228:231], v113 offset:62528
	s_nop 1
	s_waitcnt lgkmcnt(11)
	v_mfma_f32_16x16x32_bf16 v[40:43], v[236:239], v[232:235], v[36:39]
	ds_read_b128 v[236:239], v113 offset:64832
	s_nop 2
	s_waitcnt lgkmcnt(11)
	v_mfma_f32_16x16x32_bf16 v[36:39], v[240:243], v[232:235], v[44:47]
	s_nop 2
	s_waitcnt lgkmcnt(10)
	v_pk_mul_f32 v[22:23], v[22:23], v[246:247]
	v_pk_mul_f32 v[20:21], v[20:21], v[244:245]
	v_pk_mul_f32 v[24:25], v[24:25], v[244:245]
	v_pk_mul_f32 v[26:27], v[26:27], v[246:247]
	v_pk_mul_f32 v[28:29], v[28:29], v[244:245]
	v_pk_mul_f32 v[30:31], v[30:31], v[246:247]
	v_pk_mul_f32 v[32:33], v[32:33], v[244:245]
	v_pk_mul_f32 v[34:35], v[34:35], v[246:247]
	s_waitcnt lgkmcnt(8)
	v_mfma_f32_16x16x32_bf16 v[18:21], v[248:251], v[164:167], v[20:23]
	s_waitcnt lgkmcnt(7)
	v_mfma_f32_16x16x32_bf16 v[24:27], v[248:251], v[168:171], v[24:27]
	s_waitcnt lgkmcnt(6)
	v_mfma_f32_16x16x32_bf16 v[28:31], v[248:251], v[172:175], v[28:31]
	s_waitcnt lgkmcnt(5)
	v_mfma_f32_16x16x32_bf16 v[32:35], v[248:251], v[176:179], v[32:35]
	s_waitcnt lgkmcnt(3)
	v_mfma_f32_16x16x32_bf16 v[20:23], v[180:183], v[224:227], v[18:21]
	s_waitcnt lgkmcnt(2)
	v_mfma_f32_16x16x32_bf16 v[24:27], v[180:183], v[220:223], v[24:27]
	s_waitcnt lgkmcnt(1)
	v_mfma_f32_16x16x32_bf16 v[28:31], v[180:183], v[228:231], v[28:31]
	s_waitcnt lgkmcnt(0)
	v_mfma_f32_16x16x32_bf16 v[32:35], v[180:183], v[236:239], v[32:35]
	s_waitcnt vmcnt(0)
	s_and_saveexec_b64 s[74:75], vcc
	s_cbranch_execz .LBB0_374
	v_add_u32_e32 v44, s72, v71
	v_ashrrev_i32_e32 v45, 31, v44
	v_mov_b32_e32 v18, v210
	v_readlane_b32 s22, v255, 12
	v_lshlrev_b64 v[46:47], 11, v[44:45]
	v_lshlrev_b64 v[44:45], 13, v[44:45]
	v_readlane_b32 s23, v255, 13
	v_lshl_or_b32 v19, s71, 6, v46
	v_or_b32_e32 v46, v19, v66
	v_lshl_add_u64 v[44:45], s[22:23], 0, v[44:45]
	s_lshl_b32 s22, s71, 7
	s_mov_b32 s23, s12
	v_lshl_add_u64 v[44:45], v[44:45], 0, s[22:23]
	v_lshlrev_b32_e32 v16, 1, v66
	v_lshl_add_u64 v[44:45], v[44:45], 0, v[16:17]
	v_lshlrev_b64 v[50:51], 1, v[46:47]
	v_mov_b32_e32 v48, v202
	v_mov_b32_e32 v49, v203
	v_lshl_add_u64 v[52:53], s[24:25], 0, v[50:51]
	v_mov_b32_e32 v52, v204
	v_mov_b32_e32 v53, v205
	v_or_b32_e32 v46, v19, v68
	v_lshlrev_b32_e32 v54, 16, v48
	v_and_b32_e32 v55, 0xffff0000, v48
	v_lshlrev_b32_e32 v48, 16, v49
	v_and_b32_e32 v49, 0xffff0000, v49
	v_lshlrev_b32_e32 v124, 16, v52
	v_and_b32_e32 v125, 0xffff0000, v52
	v_lshlrev_b32_e32 v52, 16, v53
	v_and_b32_e32 v53, 0xffff0000, v53
	v_pk_fma_f32 v[40:41], v[18:19], v[54:55], v[40:41] op_sel_hi:[0,1,1]
	v_pk_fma_f32 v[42:43], v[18:19], v[48:49], v[42:43] op_sel_hi:[0,1,1]
	v_pk_mul_f32 v[42:43], v[42:43], v[52:53]
	v_pk_mul_f32 v[40:41], v[40:41], v[124:125]
	s_nop 0
	v_cvt_pk_bf16_f32 v40, v40, v41
	v_cvt_pk_bf16_f32 v41, v42, v43
	v_lshl_add_u64 v[42:43], s[26:27], 0, v[50:51]
	global_store_dwordx2 v[42:43], v[40:41], off
	v_lshlrev_b64 v[42:43], 1, v[46:47]
	v_mov_b32_e32 v40, v206
	v_mov_b32_e32 v41, v207
	v_lshl_add_u64 v[44:45], s[24:25], 0, v[42:43]
	v_mov_b32_e32 v44, v208
	v_mov_b32_e32 v45, v209
	v_lshlrev_b32_e32 v46, 16, v40
	v_and_b32_e32 v47, 0xffff0000, v40
	v_lshlrev_b32_e32 v40, 16, v41
	v_and_b32_e32 v41, 0xffff0000, v41
	v_lshlrev_b32_e32 v48, 16, v44
	v_and_b32_e32 v49, 0xffff0000, v44
	v_lshlrev_b32_e32 v44, 16, v45
	v_and_b32_e32 v45, 0xffff0000, v45
	v_pk_fma_f32 v[36:37], v[18:19], v[46:47], v[36:37] op_sel_hi:[0,1,1]
	v_pk_fma_f32 v[18:19], v[18:19], v[40:41], v[38:39] op_sel_hi:[0,1,1]
	v_pk_mul_f32 v[18:19], v[18:19], v[44:45]
	v_pk_mul_f32 v[36:37], v[36:37], v[48:49]
	s_nop 0
	v_cvt_pk_bf16_f32 v36, v36, v37
	v_cvt_pk_bf16_f32 v37, v18, v19
	v_lshl_add_u64 v[18:19], s[26:27], 0, v[42:43]
	global_store_dwordx2 v[18:19], v[36:37], off
